# residual epilogues: redundant int8 clamp removed before the round-to-nearest magic add (scaled values are within +-127 by construction)
# baseline (speedup 1.0000x reference)
.LBB0_1213:
	s_or_b64 exec, exec, s[58:59]
	s_waitcnt lgkmcnt(0)
	s_barrier
	s_waitcnt lgkmcnt(1)
	v_lshlrev_b64 v[2:3], 10, v[148:149]
	ds_read_b32 v0, v180 offset:8192
	ds_read_b32 v148, v181 offset:8192
	s_waitcnt lgkmcnt(2)
	ds_read_b32 v152, v182 offset:8192
	ds_read_b32 v154, v183 offset:8192
	ds_read_b32 v156, v184 offset:8192
	ds_read_b32 v158, v185 offset:8192
	ds_read_b32 v160, v186 offset:8192
	ds_read_b32 v162, v187 offset:8192
	s_waitcnt lgkmcnt(7)
	v_pk_mul_f32 v[118:119], v[118:119], v[0:1] op_sel_hi:[1,0]
	v_pk_mul_f32 v[114:115], v[114:115], v[0:1] op_sel_hi:[1,0]
	v_pk_mul_f32 v[126:127], v[126:127], v[0:1] op_sel_hi:[1,0]
	v_pk_mul_f32 v[122:123], v[122:123], v[0:1] op_sel_hi:[1,0]
	v_pk_mul_f32 v[128:129], v[128:129], v[0:1] op_sel_hi:[1,0]
	v_pk_mul_f32 v[124:125], v[124:125], v[0:1] op_sel_hi:[1,0]
	v_pk_mul_f32 v[120:121], v[120:121], v[0:1] op_sel_hi:[1,0]
	v_pk_mul_f32 v[116:117], v[116:117], v[0:1] op_sel_hi:[1,0]
	v_add_f32_e32 v0, 0x4b400000, v114
	v_add_f32_e32 v114, 0x4b400000, v115
	v_add_f32_e32 v115, 0x4b400000, v118
	v_add_f32_e32 v118, 0x4b400000, v119
	v_perm_b32 v115, v118, v115, s70
	v_perm_b32 v0, v114, v0, s70
	v_perm_b32 v114, v115, v0, s71
	v_add_f32_e32 v0, 0x4b400000, v116
	v_add_f32_e32 v115, 0x4b400000, v117
	v_add_f32_e32 v116, 0x4b400000, v120
	v_add_f32_e32 v117, 0x4b400000, v121
	v_perm_b32 v116, v117, v116, s70
	v_perm_b32 v0, v115, v0, s70
	s_waitcnt lgkmcnt(6)
	v_pk_mul_f32 v[110:111], v[110:111], v[148:149] op_sel_hi:[1,0]
	v_pk_mul_f32 v[106:107], v[106:107], v[148:149] op_sel_hi:[1,0]
	v_perm_b32 v115, v116, v0, s71
	v_add_f32_e32 v0, 0x4b400000, v106
	v_add_f32_e32 v106, 0x4b400000, v107
	v_add_f32_e32 v107, 0x4b400000, v110
	v_add_f32_e32 v110, 0x4b400000, v111
	v_pk_mul_f32 v[112:113], v[112:113], v[148:149] op_sel_hi:[1,0]
	v_pk_mul_f32 v[108:109], v[108:109], v[148:149] op_sel_hi:[1,0]
	v_perm_b32 v107, v110, v107, s70
	v_perm_b32 v0, v106, v0, s70
	v_perm_b32 v106, v107, v0, s71
	v_add_f32_e32 v0, 0x4b400000, v108
	v_add_f32_e32 v107, 0x4b400000, v109
	v_add_f32_e32 v108, 0x4b400000, v112
	v_add_f32_e32 v109, 0x4b400000, v113
	v_perm_b32 v108, v109, v108, s70
	v_perm_b32 v0, v107, v0, s70
	v_pk_mul_f32 v[102:103], v[102:103], v[148:149] op_sel_hi:[1,0]
	v_pk_mul_f32 v[98:99], v[98:99], v[148:149] op_sel_hi:[1,0]
	v_perm_b32 v107, v108, v0, s71
	v_add_f32_e32 v0, 0x4b400000, v98
	v_add_f32_e32 v98, 0x4b400000, v99
	v_add_f32_e32 v99, 0x4b400000, v102
	v_add_f32_e32 v102, 0x4b400000, v103
	v_pk_mul_f32 v[104:105], v[104:105], v[148:149] op_sel_hi:[1,0]
	v_pk_mul_f32 v[100:101], v[100:101], v[148:149] op_sel_hi:[1,0]
	v_perm_b32 v99, v102, v99, s70
	v_perm_b32 v0, v98, v0, s70
	v_perm_b32 v98, v99, v0, s71
	v_add_f32_e32 v0, 0x4b400000, v100
	v_add_f32_e32 v99, 0x4b400000, v101
	v_add_f32_e32 v100, 0x4b400000, v104
	v_add_f32_e32 v101, 0x4b400000, v105
	v_perm_b32 v100, v101, v100, s70
	v_perm_b32 v0, v99, v0, s70
	s_waitcnt lgkmcnt(5)
	v_pk_mul_f32 v[94:95], v[94:95], v[152:153] op_sel_hi:[1,0]
	v_pk_mul_f32 v[90:91], v[90:91], v[152:153] op_sel_hi:[1,0]
	v_perm_b32 v99, v100, v0, s71
	v_add_f32_e32 v0, 0x4b400000, v90
	v_add_f32_e32 v90, 0x4b400000, v91
	v_add_f32_e32 v91, 0x4b400000, v94
	v_add_f32_e32 v94, 0x4b400000, v95
	v_pk_mul_f32 v[96:97], v[96:97], v[152:153] op_sel_hi:[1,0]
	v_pk_mul_f32 v[92:93], v[92:93], v[152:153] op_sel_hi:[1,0]
	v_perm_b32 v91, v94, v91, s70
	v_perm_b32 v0, v90, v0, s70
	v_perm_b32 v90, v91, v0, s71
	v_add_f32_e32 v0, 0x4b400000, v92
	v_add_f32_e32 v91, 0x4b400000, v93
	v_add_f32_e32 v92, 0x4b400000, v96
	v_add_f32_e32 v93, 0x4b400000, v97
	v_perm_b32 v92, v93, v92, s70
	v_perm_b32 v0, v91, v0, s70
	v_pk_mul_f32 v[86:87], v[86:87], v[152:153] op_sel_hi:[1,0]
	v_pk_mul_f32 v[82:83], v[82:83], v[152:153] op_sel_hi:[1,0]
	v_perm_b32 v91, v92, v0, s71
	v_add_f32_e32 v0, 0x4b400000, v82
	v_add_f32_e32 v82, 0x4b400000, v83
	v_add_f32_e32 v83, 0x4b400000, v86
	v_add_f32_e32 v86, 0x4b400000, v87
	v_pk_mul_f32 v[88:89], v[88:89], v[152:153] op_sel_hi:[1,0]
	v_pk_mul_f32 v[84:85], v[84:85], v[152:153] op_sel_hi:[1,0]
	v_perm_b32 v83, v86, v83, s70
	v_perm_b32 v0, v82, v0, s70
	v_perm_b32 v82, v83, v0, s71
	v_add_f32_e32 v0, 0x4b400000, v84
	v_add_f32_e32 v83, 0x4b400000, v85
	v_add_f32_e32 v84, 0x4b400000, v88
	v_add_f32_e32 v85, 0x4b400000, v89
	v_perm_b32 v84, v85, v84, s70
	v_perm_b32 v0, v83, v0, s70
	s_waitcnt lgkmcnt(4)
	v_pk_mul_f32 v[78:79], v[78:79], v[154:155] op_sel_hi:[1,0]
	v_pk_mul_f32 v[74:75], v[74:75], v[154:155] op_sel_hi:[1,0]
	v_add_f32_e32 v122, 0x4b400000, v122
	v_add_f32_e32 v123, 0x4b400000, v123
	v_add_f32_e32 v126, 0x4b400000, v126
	v_add_f32_e32 v127, 0x4b400000, v127
	v_perm_b32 v83, v84, v0, s71
	v_add_f32_e32 v0, 0x4b400000, v74
	v_add_f32_e32 v74, 0x4b400000, v75
	v_add_f32_e32 v75, 0x4b400000, v78
	v_add_f32_e32 v78, 0x4b400000, v79
	v_perm_b32 v126, v127, v126, s70
	v_perm_b32 v122, v123, v122, s70
	v_pk_mul_f32 v[80:81], v[80:81], v[154:155] op_sel_hi:[1,0]
	v_pk_mul_f32 v[76:77], v[76:77], v[154:155] op_sel_hi:[1,0]
	v_perm_b32 v75, v78, v75, s70
	v_perm_b32 v0, v74, v0, s70
	v_perm_b32 v122, v126, v122, s71
	v_add_f32_e32 v123, 0x4b400000, v124
	v_add_f32_e32 v124, 0x4b400000, v125
	v_add_f32_e32 v125, 0x4b400000, v128
	v_add_f32_e32 v126, 0x4b400000, v129
	v_lshl_add_u64 v[2:3], s[26:27], 0, v[2:3]
	v_perm_b32 v74, v75, v0, s71
	v_add_f32_e32 v0, 0x4b400000, v76
	v_add_f32_e32 v75, 0x4b400000, v77
	v_add_f32_e32 v76, 0x4b400000, v80
	v_add_f32_e32 v77, 0x4b400000, v81
	v_lshl_add_u64 v[2:3], v[2:3], 0, s[60:61]
	v_perm_b32 v125, v126, v125, s70
	v_perm_b32 v123, v124, v123, s70
	v_lshl_add_u64 v[2:3], v[2:3], 0, s[34:35]
	v_perm_b32 v76, v77, v76, s70
	v_perm_b32 v0, v75, v0, s70
	v_pk_mul_f32 v[70:71], v[70:71], v[154:155] op_sel_hi:[1,0]
	v_pk_mul_f32 v[66:67], v[66:67], v[154:155] op_sel_hi:[1,0]
	v_perm_b32 v123, v125, v123, s71
	v_lshl_add_u64 v[2:3], v[2:3], 0, v[142:143]
	v_perm_b32 v75, v76, v0, s71
	v_add_f32_e32 v0, 0x4b400000, v66
	v_add_f32_e32 v66, 0x4b400000, v67
	v_add_f32_e32 v67, 0x4b400000, v70
	v_add_f32_e32 v70, 0x4b400000, v71
	global_store_dwordx2 v[2:3], v[122:123], off
	global_store_dwordx2 v[2:3], v[114:115], off offset:128
	v_add_u32_e32 v2, s45, v171
	v_ashrrev_i32_e32 v3, 31, v2
	v_pk_mul_f32 v[72:73], v[72:73], v[154:155] op_sel_hi:[1,0]
	v_pk_mul_f32 v[68:69], v[68:69], v[154:155] op_sel_hi:[1,0]
	v_perm_b32 v67, v70, v67, s70
	v_perm_b32 v0, v66, v0, s70
	v_lshlrev_b64 v[2:3], 10, v[2:3]
	v_perm_b32 v66, v67, v0, s71
	v_add_f32_e32 v0, 0x4b400000, v68
	v_add_f32_e32 v67, 0x4b400000, v69
	v_add_f32_e32 v68, 0x4b400000, v72
	v_add_f32_e32 v69, 0x4b400000, v73
	v_lshl_add_u64 v[2:3], s[26:27], 0, v[2:3]
	v_lshl_add_u64 v[2:3], v[2:3], 0, s[60:61]
	v_perm_b32 v68, v69, v68, s70
	v_perm_b32 v0, v67, v0, s70
	s_waitcnt lgkmcnt(3)
	v_pk_mul_f32 v[62:63], v[62:63], v[156:157] op_sel_hi:[1,0]
	v_pk_mul_f32 v[58:59], v[58:59], v[156:157] op_sel_hi:[1,0]
	v_lshl_add_u64 v[2:3], v[2:3], 0, s[34:35]
	v_perm_b32 v67, v68, v0, s71
	v_add_f32_e32 v0, 0x4b400000, v58
	v_add_f32_e32 v58, 0x4b400000, v59
	v_add_f32_e32 v59, 0x4b400000, v62
	v_add_f32_e32 v62, 0x4b400000, v63
	v_lshl_add_u64 v[2:3], v[2:3], 0, v[142:143]
	global_store_dwordx2 v[2:3], v[106:107], off
	global_store_dwordx2 v[2:3], v[98:99], off offset:128
	v_add_u32_e32 v2, s45, v172
	v_pk_mul_f32 v[64:65], v[64:65], v[156:157] op_sel_hi:[1,0]
	v_pk_mul_f32 v[60:61], v[60:61], v[156:157] op_sel_hi:[1,0]
	v_perm_b32 v59, v62, v59, s70
	v_perm_b32 v0, v58, v0, s70
	v_ashrrev_i32_e32 v3, 31, v2
	v_perm_b32 v58, v59, v0, s71
	v_add_f32_e32 v0, 0x4b400000, v60
	v_add_f32_e32 v59, 0x4b400000, v61
	v_add_f32_e32 v60, 0x4b400000, v64
	v_add_f32_e32 v61, 0x4b400000, v65
	v_lshlrev_b64 v[2:3], 10, v[2:3]
	v_lshl_add_u64 v[2:3], s[26:27], 0, v[2:3]
	v_perm_b32 v60, v61, v60, s70
	v_perm_b32 v0, v59, v0, s70
	v_pk_mul_f32 v[54:55], v[54:55], v[156:157] op_sel_hi:[1,0]
	v_pk_mul_f32 v[50:51], v[50:51], v[156:157] op_sel_hi:[1,0]
	v_lshl_add_u64 v[2:3], v[2:3], 0, s[60:61]
	v_perm_b32 v59, v60, v0, s71
	v_add_f32_e32 v0, 0x4b400000, v50
	v_add_f32_e32 v50, 0x4b400000, v51
	v_add_f32_e32 v51, 0x4b400000, v54
	v_add_f32_e32 v54, 0x4b400000, v55
	v_lshl_add_u64 v[2:3], v[2:3], 0, s[34:35]
	v_lshl_add_u64 v[2:3], v[2:3], 0, v[142:143]
	v_pk_mul_f32 v[56:57], v[56:57], v[156:157] op_sel_hi:[1,0]
	v_pk_mul_f32 v[52:53], v[52:53], v[156:157] op_sel_hi:[1,0]
	v_perm_b32 v51, v54, v51, s70
	v_perm_b32 v0, v50, v0, s70
	global_store_dwordx2 v[2:3], v[90:91], off
	global_store_dwordx2 v[2:3], v[82:83], off offset:128
	v_add_u32_e32 v2, s45, v173
	v_perm_b32 v50, v51, v0, s71
	v_add_f32_e32 v0, 0x4b400000, v52
	v_add_f32_e32 v51, 0x4b400000, v53
	v_add_f32_e32 v52, 0x4b400000, v56
	v_add_f32_e32 v53, 0x4b400000, v57
	v_ashrrev_i32_e32 v3, 31, v2
	v_lshlrev_b64 v[2:3], 10, v[2:3]
	v_perm_b32 v52, v53, v52, s70
	v_perm_b32 v0, v51, v0, s70
	s_waitcnt lgkmcnt(2)
	v_pk_mul_f32 v[46:47], v[46:47], v[158:159] op_sel_hi:[1,0]
	v_pk_mul_f32 v[42:43], v[42:43], v[158:159] op_sel_hi:[1,0]
	v_lshl_add_u64 v[2:3], s[26:27], 0, v[2:3]
	v_perm_b32 v51, v52, v0, s71
	v_add_f32_e32 v0, 0x4b400000, v42
	v_add_f32_e32 v42, 0x4b400000, v43
	v_add_f32_e32 v43, 0x4b400000, v46
	v_add_f32_e32 v46, 0x4b400000, v47
	v_lshl_add_u64 v[2:3], v[2:3], 0, s[60:61]
	v_lshl_add_u64 v[2:3], v[2:3], 0, s[34:35]
	v_pk_mul_f32 v[48:49], v[48:49], v[158:159] op_sel_hi:[1,0]
	v_pk_mul_f32 v[44:45], v[44:45], v[158:159] op_sel_hi:[1,0]
	v_perm_b32 v43, v46, v43, s70
	v_perm_b32 v0, v42, v0, s70
	v_lshl_add_u64 v[2:3], v[2:3], 0, v[142:143]
	v_perm_b32 v42, v43, v0, s71
	v_add_f32_e32 v0, 0x4b400000, v44
	v_add_f32_e32 v43, 0x4b400000, v45
	v_add_f32_e32 v44, 0x4b400000, v48
	v_add_f32_e32 v45, 0x4b400000, v49
	global_store_dwordx2 v[2:3], v[74:75], off
	global_store_dwordx2 v[2:3], v[66:67], off offset:128
	v_add_u32_e32 v2, s45, v170
	v_ashrrev_i32_e32 v3, 31, v2
	v_perm_b32 v44, v45, v44, s70
	v_perm_b32 v0, v43, v0, s70
	v_pk_mul_f32 v[38:39], v[38:39], v[158:159] op_sel_hi:[1,0]
	v_pk_mul_f32 v[34:35], v[34:35], v[158:159] op_sel_hi:[1,0]
	v_lshlrev_b64 v[2:3], 10, v[2:3]
	v_perm_b32 v43, v44, v0, s71
	v_add_f32_e32 v0, 0x4b400000, v34
	v_add_f32_e32 v34, 0x4b400000, v35
	v_add_f32_e32 v35, 0x4b400000, v38
	v_add_f32_e32 v38, 0x4b400000, v39
	v_lshl_add_u64 v[2:3], s[26:27], 0, v[2:3]
	v_lshl_add_u64 v[2:3], v[2:3], 0, s[60:61]
	v_pk_mul_f32 v[40:41], v[40:41], v[158:159] op_sel_hi:[1,0]
	v_pk_mul_f32 v[36:37], v[36:37], v[158:159] op_sel_hi:[1,0]
	v_perm_b32 v35, v38, v35, s70
	v_perm_b32 v0, v34, v0, s70
	v_lshl_add_u64 v[2:3], v[2:3], 0, s[34:35]
	v_perm_b32 v34, v35, v0, s71
	v_add_f32_e32 v0, 0x4b400000, v36
	v_add_f32_e32 v35, 0x4b400000, v37
	v_add_f32_e32 v36, 0x4b400000, v40
	v_add_f32_e32 v37, 0x4b400000, v41
	v_lshl_add_u64 v[2:3], v[2:3], 0, v[142:143]
	global_store_dwordx2 v[2:3], v[58:59], off
	global_store_dwordx2 v[2:3], v[50:51], off offset:128
	v_add_u32_e32 v2, s45, v174
	v_perm_b32 v36, v37, v36, s70
	v_perm_b32 v0, v35, v0, s70
	s_waitcnt lgkmcnt(1)
	v_pk_mul_f32 v[30:31], v[30:31], v[160:161] op_sel_hi:[1,0]
	v_pk_mul_f32 v[26:27], v[26:27], v[160:161] op_sel_hi:[1,0]
	v_ashrrev_i32_e32 v3, 31, v2
	v_perm_b32 v35, v36, v0, s71
	v_add_f32_e32 v0, 0x4b400000, v26
	v_add_f32_e32 v26, 0x4b400000, v27
	v_add_f32_e32 v27, 0x4b400000, v30
	v_add_f32_e32 v30, 0x4b400000, v31
	v_lshlrev_b64 v[2:3], 10, v[2:3]
	v_lshl_add_u64 v[2:3], s[26:27], 0, v[2:3]
	v_pk_mul_f32 v[32:33], v[32:33], v[160:161] op_sel_hi:[1,0]
	v_pk_mul_f32 v[28:29], v[28:29], v[160:161] op_sel_hi:[1,0]
	v_perm_b32 v27, v30, v27, s70
	v_perm_b32 v0, v26, v0, s70
	v_lshl_add_u64 v[2:3], v[2:3], 0, s[60:61]
	v_perm_b32 v26, v27, v0, s71
	v_add_f32_e32 v0, 0x4b400000, v28
	v_add_f32_e32 v27, 0x4b400000, v29
	v_add_f32_e32 v28, 0x4b400000, v32
	v_add_f32_e32 v29, 0x4b400000, v33
	v_lshl_add_u64 v[2:3], v[2:3], 0, s[34:35]
	v_lshl_add_u64 v[2:3], v[2:3], 0, v[142:143]
	v_perm_b32 v28, v29, v28, s70
	v_perm_b32 v0, v27, v0, s70
	v_pk_mul_f32 v[22:23], v[22:23], v[160:161] op_sel_hi:[1,0]
	v_pk_mul_f32 v[18:19], v[18:19], v[160:161] op_sel_hi:[1,0]
	global_store_dwordx2 v[2:3], v[42:43], off
	global_store_dwordx2 v[2:3], v[34:35], off offset:128
	v_add_u32_e32 v2, s45, v175
	v_perm_b32 v27, v28, v0, s71
	v_add_f32_e32 v0, 0x4b400000, v18
	v_add_f32_e32 v18, 0x4b400000, v19
	v_add_f32_e32 v19, 0x4b400000, v22
	v_add_f32_e32 v22, 0x4b400000, v23
	v_ashrrev_i32_e32 v3, 31, v2
	v_lshlrev_b64 v[2:3], 10, v[2:3]
	v_pk_mul_f32 v[24:25], v[24:25], v[160:161] op_sel_hi:[1,0]
	v_pk_mul_f32 v[20:21], v[20:21], v[160:161] op_sel_hi:[1,0]
	v_perm_b32 v19, v22, v19, s70
	v_perm_b32 v0, v18, v0, s70
	v_lshl_add_u64 v[2:3], s[26:27], 0, v[2:3]
	v_perm_b32 v18, v19, v0, s71
	v_add_f32_e32 v0, 0x4b400000, v20
	v_add_f32_e32 v19, 0x4b400000, v21
	v_add_f32_e32 v20, 0x4b400000, v24
	v_add_f32_e32 v21, 0x4b400000, v25
	v_lshl_add_u64 v[2:3], v[2:3], 0, s[60:61]
	v_lshl_add_u64 v[2:3], v[2:3], 0, s[34:35]
	v_perm_b32 v20, v21, v20, s70
	v_perm_b32 v0, v19, v0, s70
	v_lshl_add_u64 v[2:3], v[2:3], 0, v[142:143]
	v_perm_b32 v19, v20, v0, s71
	global_store_dwordx2 v[2:3], v[18:19], off offset:128
	s_waitcnt lgkmcnt(0)
	v_pk_mul_f32 v[18:19], v[150:151], v[162:163] op_sel_hi:[1,0]
	v_pk_mul_f32 v[14:15], v[14:15], v[162:163] op_sel_hi:[1,0]
	v_pk_mul_f32 v[16:17], v[16:17], v[162:163] op_sel_hi:[1,0]
	v_add_f32_e32 v0, 0x4b400000, v14
	v_add_f32_e32 v14, 0x4b400000, v15
	v_add_f32_e32 v15, 0x4b400000, v18
	v_add_f32_e32 v18, 0x4b400000, v19
	v_pk_mul_f32 v[12:13], v[12:13], v[162:163] op_sel_hi:[1,0]
	v_perm_b32 v15, v18, v15, s70
	v_perm_b32 v0, v14, v0, s70
	v_perm_b32 v14, v15, v0, s71
	v_add_f32_e32 v0, 0x4b400000, v12
	v_add_f32_e32 v12, 0x4b400000, v13
	v_add_f32_e32 v13, 0x4b400000, v16
	v_add_f32_e32 v15, 0x4b400000, v17
	v_perm_b32 v13, v15, v13, s70
	v_perm_b32 v0, v12, v0, s70
	v_pk_mul_f32 v[10:11], v[10:11], v[162:163] op_sel_hi:[1,0]
	v_pk_mul_f32 v[6:7], v[6:7], v[162:163] op_sel_hi:[1,0]
	global_store_dwordx2 v[2:3], v[26:27], off
	v_add_u32_e32 v2, s45, v176
	v_perm_b32 v15, v13, v0, s71
	v_add_f32_e32 v0, 0x4b400000, v6
	v_add_f32_e32 v6, 0x4b400000, v7
	v_add_f32_e32 v7, 0x4b400000, v10
	v_add_f32_e32 v10, 0x4b400000, v11
	v_ashrrev_i32_e32 v3, 31, v2
	v_lshlrev_b64 v[2:3], 10, v[2:3]
	v_pk_mul_f32 v[8:9], v[8:9], v[162:163] op_sel_hi:[1,0]
	v_pk_mul_f32 v[4:5], v[4:5], v[162:163] op_sel_hi:[1,0]
	v_perm_b32 v7, v10, v7, s70
	v_perm_b32 v0, v6, v0, s70
	v_lshl_add_u64 v[2:3], s[26:27], 0, v[2:3]
	v_perm_b32 v6, v7, v0, s71
	v_add_f32_e32 v0, 0x4b400000, v4
	v_add_f32_e32 v4, 0x4b400000, v5
	v_add_f32_e32 v5, 0x4b400000, v8
	v_add_f32_e32 v7, 0x4b400000, v9
	v_lshl_add_u64 v[2:3], v[2:3], 0, s[60:61]
	v_lshl_add_u64 v[2:3], v[2:3], 0, s[34:35]
	v_perm_b32 v5, v7, v5, s70
	v_perm_b32 v0, v4, v0, s70
	v_lshl_add_u64 v[2:3], v[2:3], 0, v[142:143]
	v_perm_b32 v7, v5, v0, s71
	global_store_dwordx2 v[2:3], v[14:15], off
	global_store_dwordx2 v[2:3], v[6:7], off offset:128

.LBB0_1682:
	s_or_b64 exec, exec, s[58:59]
	s_waitcnt lgkmcnt(0)
	s_barrier
	s_waitcnt lgkmcnt(1)
	v_lshlrev_b64 v[2:3], 10, v[148:149]
	ds_read_b32 v0, v180 offset:8192
	ds_read_b32 v148, v181 offset:8192
	s_waitcnt lgkmcnt(2)
	ds_read_b32 v152, v182 offset:8192
	ds_read_b32 v154, v183 offset:8192
	ds_read_b32 v156, v184 offset:8192
	ds_read_b32 v158, v185 offset:8192
	ds_read_b32 v160, v186 offset:8192
	ds_read_b32 v162, v187 offset:8192
	s_waitcnt lgkmcnt(7)
	v_pk_mul_f32 v[118:119], v[118:119], v[0:1] op_sel_hi:[1,0]
	v_pk_mul_f32 v[114:115], v[114:115], v[0:1] op_sel_hi:[1,0]
	v_pk_mul_f32 v[126:127], v[126:127], v[0:1] op_sel_hi:[1,0]
	v_pk_mul_f32 v[122:123], v[122:123], v[0:1] op_sel_hi:[1,0]
	v_pk_mul_f32 v[128:129], v[128:129], v[0:1] op_sel_hi:[1,0]
	v_pk_mul_f32 v[124:125], v[124:125], v[0:1] op_sel_hi:[1,0]
	v_pk_mul_f32 v[120:121], v[120:121], v[0:1] op_sel_hi:[1,0]
	v_pk_mul_f32 v[116:117], v[116:117], v[0:1] op_sel_hi:[1,0]
	v_add_f32_e32 v0, 0x4b400000, v114
	v_add_f32_e32 v114, 0x4b400000, v115
	v_add_f32_e32 v115, 0x4b400000, v118
	v_add_f32_e32 v118, 0x4b400000, v119
	v_perm_b32 v115, v118, v115, s70
	v_perm_b32 v0, v114, v0, s70
	v_perm_b32 v114, v115, v0, s71
	v_add_f32_e32 v0, 0x4b400000, v116
	v_add_f32_e32 v115, 0x4b400000, v117
	v_add_f32_e32 v116, 0x4b400000, v120
	v_add_f32_e32 v117, 0x4b400000, v121
	v_perm_b32 v116, v117, v116, s70
	v_perm_b32 v0, v115, v0, s70
	s_waitcnt lgkmcnt(6)
	v_pk_mul_f32 v[110:111], v[110:111], v[148:149] op_sel_hi:[1,0]
	v_pk_mul_f32 v[106:107], v[106:107], v[148:149] op_sel_hi:[1,0]
	v_perm_b32 v115, v116, v0, s71
	v_add_f32_e32 v0, 0x4b400000, v106
	v_add_f32_e32 v106, 0x4b400000, v107
	v_add_f32_e32 v107, 0x4b400000, v110
	v_add_f32_e32 v110, 0x4b400000, v111
	v_pk_mul_f32 v[112:113], v[112:113], v[148:149] op_sel_hi:[1,0]
	v_pk_mul_f32 v[108:109], v[108:109], v[148:149] op_sel_hi:[1,0]
	v_perm_b32 v107, v110, v107, s70
	v_perm_b32 v0, v106, v0, s70
	v_perm_b32 v106, v107, v0, s71
	v_add_f32_e32 v0, 0x4b400000, v108
	v_add_f32_e32 v107, 0x4b400000, v109
	v_add_f32_e32 v108, 0x4b400000, v112
	v_add_f32_e32 v109, 0x4b400000, v113
	v_perm_b32 v108, v109, v108, s70
	v_perm_b32 v0, v107, v0, s70
	v_pk_mul_f32 v[102:103], v[102:103], v[148:149] op_sel_hi:[1,0]
	v_pk_mul_f32 v[98:99], v[98:99], v[148:149] op_sel_hi:[1,0]
	v_perm_b32 v107, v108, v0, s71
	v_add_f32_e32 v0, 0x4b400000, v98
	v_add_f32_e32 v98, 0x4b400000, v99
	v_add_f32_e32 v99, 0x4b400000, v102
	v_add_f32_e32 v102, 0x4b400000, v103
	v_pk_mul_f32 v[104:105], v[104:105], v[148:149] op_sel_hi:[1,0]
	v_pk_mul_f32 v[100:101], v[100:101], v[148:149] op_sel_hi:[1,0]
	v_perm_b32 v99, v102, v99, s70
	v_perm_b32 v0, v98, v0, s70
	v_perm_b32 v98, v99, v0, s71
	v_add_f32_e32 v0, 0x4b400000, v100
	v_add_f32_e32 v99, 0x4b400000, v101
	v_add_f32_e32 v100, 0x4b400000, v104
	v_add_f32_e32 v101, 0x4b400000, v105
	v_perm_b32 v100, v101, v100, s70
	v_perm_b32 v0, v99, v0, s70
	s_waitcnt lgkmcnt(5)
	v_pk_mul_f32 v[94:95], v[94:95], v[152:153] op_sel_hi:[1,0]
	v_pk_mul_f32 v[90:91], v[90:91], v[152:153] op_sel_hi:[1,0]
	v_perm_b32 v99, v100, v0, s71
	v_add_f32_e32 v0, 0x4b400000, v90
	v_add_f32_e32 v90, 0x4b400000, v91
	v_add_f32_e32 v91, 0x4b400000, v94
	v_add_f32_e32 v94, 0x4b400000, v95
	v_pk_mul_f32 v[96:97], v[96:97], v[152:153] op_sel_hi:[1,0]
	v_pk_mul_f32 v[92:93], v[92:93], v[152:153] op_sel_hi:[1,0]
	v_perm_b32 v91, v94, v91, s70
	v_perm_b32 v0, v90, v0, s70
	v_perm_b32 v90, v91, v0, s71
	v_add_f32_e32 v0, 0x4b400000, v92
	v_add_f32_e32 v91, 0x4b400000, v93
	v_add_f32_e32 v92, 0x4b400000, v96
	v_add_f32_e32 v93, 0x4b400000, v97
	v_perm_b32 v92, v93, v92, s70
	v_perm_b32 v0, v91, v0, s70
	v_pk_mul_f32 v[86:87], v[86:87], v[152:153] op_sel_hi:[1,0]
	v_pk_mul_f32 v[82:83], v[82:83], v[152:153] op_sel_hi:[1,0]
	v_perm_b32 v91, v92, v0, s71
	v_add_f32_e32 v0, 0x4b400000, v82
	v_add_f32_e32 v82, 0x4b400000, v83
	v_add_f32_e32 v83, 0x4b400000, v86
	v_add_f32_e32 v86, 0x4b400000, v87
	v_pk_mul_f32 v[88:89], v[88:89], v[152:153] op_sel_hi:[1,0]
	v_pk_mul_f32 v[84:85], v[84:85], v[152:153] op_sel_hi:[1,0]
	v_perm_b32 v83, v86, v83, s70
	v_perm_b32 v0, v82, v0, s70
	v_perm_b32 v82, v83, v0, s71
	v_add_f32_e32 v0, 0x4b400000, v84
	v_add_f32_e32 v83, 0x4b400000, v85
	v_add_f32_e32 v84, 0x4b400000, v88
	v_add_f32_e32 v85, 0x4b400000, v89
	v_perm_b32 v84, v85, v84, s70
	v_perm_b32 v0, v83, v0, s70
	s_waitcnt lgkmcnt(4)
	v_pk_mul_f32 v[78:79], v[78:79], v[154:155] op_sel_hi:[1,0]
	v_pk_mul_f32 v[74:75], v[74:75], v[154:155] op_sel_hi:[1,0]
	v_add_f32_e32 v122, 0x4b400000, v122
	v_add_f32_e32 v123, 0x4b400000, v123
	v_add_f32_e32 v126, 0x4b400000, v126
	v_add_f32_e32 v127, 0x4b400000, v127
	v_perm_b32 v83, v84, v0, s71
	v_add_f32_e32 v0, 0x4b400000, v74
	v_add_f32_e32 v74, 0x4b400000, v75
	v_add_f32_e32 v75, 0x4b400000, v78
	v_add_f32_e32 v78, 0x4b400000, v79
	v_perm_b32 v126, v127, v126, s70
	v_perm_b32 v122, v123, v122, s70
	v_pk_mul_f32 v[80:81], v[80:81], v[154:155] op_sel_hi:[1,0]
	v_pk_mul_f32 v[76:77], v[76:77], v[154:155] op_sel_hi:[1,0]
	v_perm_b32 v75, v78, v75, s70
	v_perm_b32 v0, v74, v0, s70
	v_perm_b32 v122, v126, v122, s71
	v_add_f32_e32 v123, 0x4b400000, v124
	v_add_f32_e32 v124, 0x4b400000, v125
	v_add_f32_e32 v125, 0x4b400000, v128
	v_add_f32_e32 v126, 0x4b400000, v129
	v_lshl_add_u64 v[2:3], s[30:31], 0, v[2:3]
	v_perm_b32 v74, v75, v0, s71
	v_add_f32_e32 v0, 0x4b400000, v76
	v_add_f32_e32 v75, 0x4b400000, v77
	v_add_f32_e32 v76, 0x4b400000, v80
	v_add_f32_e32 v77, 0x4b400000, v81
	v_lshl_add_u64 v[2:3], v[2:3], 0, s[56:57]
	v_perm_b32 v125, v126, v125, s70
	v_perm_b32 v123, v124, v123, s70
	v_lshl_add_u64 v[2:3], v[2:3], 0, s[40:41]
	v_perm_b32 v76, v77, v76, s70
	v_perm_b32 v0, v75, v0, s70
	v_pk_mul_f32 v[70:71], v[70:71], v[154:155] op_sel_hi:[1,0]
	v_pk_mul_f32 v[66:67], v[66:67], v[154:155] op_sel_hi:[1,0]
	v_perm_b32 v123, v125, v123, s71
	v_lshl_add_u64 v[2:3], v[2:3], 0, v[142:143]
	v_perm_b32 v75, v76, v0, s71
	v_add_f32_e32 v0, 0x4b400000, v66
	v_add_f32_e32 v66, 0x4b400000, v67
	v_add_f32_e32 v67, 0x4b400000, v70
	v_add_f32_e32 v70, 0x4b400000, v71
	global_store_dwordx2 v[2:3], v[122:123], off
	global_store_dwordx2 v[2:3], v[114:115], off offset:128
	v_add_u32_e32 v2, s91, v171
	v_ashrrev_i32_e32 v3, 31, v2
	v_pk_mul_f32 v[72:73], v[72:73], v[154:155] op_sel_hi:[1,0]
	v_pk_mul_f32 v[68:69], v[68:69], v[154:155] op_sel_hi:[1,0]
	v_perm_b32 v67, v70, v67, s70
	v_perm_b32 v0, v66, v0, s70
	v_lshlrev_b64 v[2:3], 10, v[2:3]
	v_perm_b32 v66, v67, v0, s71
	v_add_f32_e32 v0, 0x4b400000, v68
	v_add_f32_e32 v67, 0x4b400000, v69
	v_add_f32_e32 v68, 0x4b400000, v72
	v_add_f32_e32 v69, 0x4b400000, v73
	v_lshl_add_u64 v[2:3], s[30:31], 0, v[2:3]
	v_lshl_add_u64 v[2:3], v[2:3], 0, s[56:57]
	v_perm_b32 v68, v69, v68, s70
	v_perm_b32 v0, v67, v0, s70
	s_waitcnt lgkmcnt(3)
	v_pk_mul_f32 v[62:63], v[62:63], v[156:157] op_sel_hi:[1,0]
	v_pk_mul_f32 v[58:59], v[58:59], v[156:157] op_sel_hi:[1,0]
	v_lshl_add_u64 v[2:3], v[2:3], 0, s[40:41]
	v_perm_b32 v67, v68, v0, s71
	v_add_f32_e32 v0, 0x4b400000, v58
	v_add_f32_e32 v58, 0x4b400000, v59
	v_add_f32_e32 v59, 0x4b400000, v62
	v_add_f32_e32 v62, 0x4b400000, v63
	v_lshl_add_u64 v[2:3], v[2:3], 0, v[142:143]
	global_store_dwordx2 v[2:3], v[106:107], off
	global_store_dwordx2 v[2:3], v[98:99], off offset:128
	v_add_u32_e32 v2, s91, v172
	v_pk_mul_f32 v[64:65], v[64:65], v[156:157] op_sel_hi:[1,0]
	v_pk_mul_f32 v[60:61], v[60:61], v[156:157] op_sel_hi:[1,0]
	v_perm_b32 v59, v62, v59, s70
	v_perm_b32 v0, v58, v0, s70
	v_ashrrev_i32_e32 v3, 31, v2
	v_perm_b32 v58, v59, v0, s71
	v_add_f32_e32 v0, 0x4b400000, v60
	v_add_f32_e32 v59, 0x4b400000, v61
	v_add_f32_e32 v60, 0x4b400000, v64
	v_add_f32_e32 v61, 0x4b400000, v65
	v_lshlrev_b64 v[2:3], 10, v[2:3]
	v_lshl_add_u64 v[2:3], s[30:31], 0, v[2:3]
	v_perm_b32 v60, v61, v60, s70
	v_perm_b32 v0, v59, v0, s70
	v_pk_mul_f32 v[54:55], v[54:55], v[156:157] op_sel_hi:[1,0]
	v_pk_mul_f32 v[50:51], v[50:51], v[156:157] op_sel_hi:[1,0]
	v_lshl_add_u64 v[2:3], v[2:3], 0, s[56:57]
	v_perm_b32 v59, v60, v0, s71
	v_add_f32_e32 v0, 0x4b400000, v50
	v_add_f32_e32 v50, 0x4b400000, v51
	v_add_f32_e32 v51, 0x4b400000, v54
	v_add_f32_e32 v54, 0x4b400000, v55
	v_lshl_add_u64 v[2:3], v[2:3], 0, s[40:41]
	v_lshl_add_u64 v[2:3], v[2:3], 0, v[142:143]
	v_pk_mul_f32 v[56:57], v[56:57], v[156:157] op_sel_hi:[1,0]
	v_pk_mul_f32 v[52:53], v[52:53], v[156:157] op_sel_hi:[1,0]
	v_perm_b32 v51, v54, v51, s70
	v_perm_b32 v0, v50, v0, s70
	global_store_dwordx2 v[2:3], v[90:91], off
	global_store_dwordx2 v[2:3], v[82:83], off offset:128
	v_add_u32_e32 v2, s91, v173
	v_perm_b32 v50, v51, v0, s71
	v_add_f32_e32 v0, 0x4b400000, v52
	v_add_f32_e32 v51, 0x4b400000, v53
	v_add_f32_e32 v52, 0x4b400000, v56
	v_add_f32_e32 v53, 0x4b400000, v57
	v_ashrrev_i32_e32 v3, 31, v2
	v_lshlrev_b64 v[2:3], 10, v[2:3]
	v_perm_b32 v52, v53, v52, s70
	v_perm_b32 v0, v51, v0, s70
	s_waitcnt lgkmcnt(2)
	v_pk_mul_f32 v[46:47], v[46:47], v[158:159] op_sel_hi:[1,0]
	v_pk_mul_f32 v[42:43], v[42:43], v[158:159] op_sel_hi:[1,0]
	v_lshl_add_u64 v[2:3], s[30:31], 0, v[2:3]
	v_perm_b32 v51, v52, v0, s71
	v_add_f32_e32 v0, 0x4b400000, v42
	v_add_f32_e32 v42, 0x4b400000, v43
	v_add_f32_e32 v43, 0x4b400000, v46
	v_add_f32_e32 v46, 0x4b400000, v47
	v_lshl_add_u64 v[2:3], v[2:3], 0, s[56:57]
	v_lshl_add_u64 v[2:3], v[2:3], 0, s[40:41]
	v_pk_mul_f32 v[48:49], v[48:49], v[158:159] op_sel_hi:[1,0]
	v_pk_mul_f32 v[44:45], v[44:45], v[158:159] op_sel_hi:[1,0]
	v_perm_b32 v43, v46, v43, s70
	v_perm_b32 v0, v42, v0, s70
	v_lshl_add_u64 v[2:3], v[2:3], 0, v[142:143]
	v_perm_b32 v42, v43, v0, s71
	v_add_f32_e32 v0, 0x4b400000, v44
	v_add_f32_e32 v43, 0x4b400000, v45
	v_add_f32_e32 v44, 0x4b400000, v48
	v_add_f32_e32 v45, 0x4b400000, v49
	global_store_dwordx2 v[2:3], v[74:75], off
	global_store_dwordx2 v[2:3], v[66:67], off offset:128
	v_add_u32_e32 v2, s91, v170
	v_ashrrev_i32_e32 v3, 31, v2
	v_perm_b32 v44, v45, v44, s70
	v_perm_b32 v0, v43, v0, s70
	v_pk_mul_f32 v[38:39], v[38:39], v[158:159] op_sel_hi:[1,0]
	v_pk_mul_f32 v[34:35], v[34:35], v[158:159] op_sel_hi:[1,0]
	v_lshlrev_b64 v[2:3], 10, v[2:3]
	v_perm_b32 v43, v44, v0, s71
	v_add_f32_e32 v0, 0x4b400000, v34
	v_add_f32_e32 v34, 0x4b400000, v35
	v_add_f32_e32 v35, 0x4b400000, v38
	v_add_f32_e32 v38, 0x4b400000, v39
	v_lshl_add_u64 v[2:3], s[30:31], 0, v[2:3]
	v_lshl_add_u64 v[2:3], v[2:3], 0, s[56:57]
	v_pk_mul_f32 v[40:41], v[40:41], v[158:159] op_sel_hi:[1,0]
	v_pk_mul_f32 v[36:37], v[36:37], v[158:159] op_sel_hi:[1,0]
	v_perm_b32 v35, v38, v35, s70
	v_perm_b32 v0, v34, v0, s70
	v_lshl_add_u64 v[2:3], v[2:3], 0, s[40:41]
	v_perm_b32 v34, v35, v0, s71
	v_add_f32_e32 v0, 0x4b400000, v36
	v_add_f32_e32 v35, 0x4b400000, v37
	v_add_f32_e32 v36, 0x4b400000, v40
	v_add_f32_e32 v37, 0x4b400000, v41
	v_lshl_add_u64 v[2:3], v[2:3], 0, v[142:143]
	global_store_dwordx2 v[2:3], v[58:59], off
	global_store_dwordx2 v[2:3], v[50:51], off offset:128
	v_add_u32_e32 v2, s91, v174
	v_perm_b32 v36, v37, v36, s70
	v_perm_b32 v0, v35, v0, s70
	s_waitcnt lgkmcnt(1)
	v_pk_mul_f32 v[30:31], v[30:31], v[160:161] op_sel_hi:[1,0]
	v_pk_mul_f32 v[26:27], v[26:27], v[160:161] op_sel_hi:[1,0]
	v_ashrrev_i32_e32 v3, 31, v2
	v_perm_b32 v35, v36, v0, s71
	v_add_f32_e32 v0, 0x4b400000, v26
	v_add_f32_e32 v26, 0x4b400000, v27
	v_add_f32_e32 v27, 0x4b400000, v30
	v_add_f32_e32 v30, 0x4b400000, v31
	v_lshlrev_b64 v[2:3], 10, v[2:3]
	v_lshl_add_u64 v[2:3], s[30:31], 0, v[2:3]
	v_pk_mul_f32 v[32:33], v[32:33], v[160:161] op_sel_hi:[1,0]
	v_pk_mul_f32 v[28:29], v[28:29], v[160:161] op_sel_hi:[1,0]
	v_perm_b32 v27, v30, v27, s70
	v_perm_b32 v0, v26, v0, s70
	v_lshl_add_u64 v[2:3], v[2:3], 0, s[56:57]
	v_perm_b32 v26, v27, v0, s71
	v_add_f32_e32 v0, 0x4b400000, v28
	v_add_f32_e32 v27, 0x4b400000, v29
	v_add_f32_e32 v28, 0x4b400000, v32
	v_add_f32_e32 v29, 0x4b400000, v33
	v_lshl_add_u64 v[2:3], v[2:3], 0, s[40:41]
	v_lshl_add_u64 v[2:3], v[2:3], 0, v[142:143]
	v_perm_b32 v28, v29, v28, s70
	v_perm_b32 v0, v27, v0, s70
	v_pk_mul_f32 v[22:23], v[22:23], v[160:161] op_sel_hi:[1,0]
	v_pk_mul_f32 v[18:19], v[18:19], v[160:161] op_sel_hi:[1,0]
	global_store_dwordx2 v[2:3], v[42:43], off
	global_store_dwordx2 v[2:3], v[34:35], off offset:128
	v_add_u32_e32 v2, s91, v175
	v_perm_b32 v27, v28, v0, s71
	v_add_f32_e32 v0, 0x4b400000, v18
	v_add_f32_e32 v18, 0x4b400000, v19
	v_add_f32_e32 v19, 0x4b400000, v22
	v_add_f32_e32 v22, 0x4b400000, v23
	v_ashrrev_i32_e32 v3, 31, v2
	v_lshlrev_b64 v[2:3], 10, v[2:3]
	v_pk_mul_f32 v[24:25], v[24:25], v[160:161] op_sel_hi:[1,0]
	v_pk_mul_f32 v[20:21], v[20:21], v[160:161] op_sel_hi:[1,0]
	v_perm_b32 v19, v22, v19, s70
	v_perm_b32 v0, v18, v0, s70
	v_lshl_add_u64 v[2:3], s[30:31], 0, v[2:3]
	v_perm_b32 v18, v19, v0, s71
	v_add_f32_e32 v0, 0x4b400000, v20
	v_add_f32_e32 v19, 0x4b400000, v21
	v_add_f32_e32 v20, 0x4b400000, v24
	v_add_f32_e32 v21, 0x4b400000, v25
	v_lshl_add_u64 v[2:3], v[2:3], 0, s[56:57]
	v_lshl_add_u64 v[2:3], v[2:3], 0, s[40:41]
	v_perm_b32 v20, v21, v20, s70
	v_perm_b32 v0, v19, v0, s70
	v_lshl_add_u64 v[2:3], v[2:3], 0, v[142:143]
	v_perm_b32 v19, v20, v0, s71
	global_store_dwordx2 v[2:3], v[18:19], off offset:128
	s_waitcnt lgkmcnt(0)
	v_pk_mul_f32 v[18:19], v[150:151], v[162:163] op_sel_hi:[1,0]
	v_pk_mul_f32 v[14:15], v[14:15], v[162:163] op_sel_hi:[1,0]
	v_pk_mul_f32 v[16:17], v[16:17], v[162:163] op_sel_hi:[1,0]
	v_add_f32_e32 v0, 0x4b400000, v14
	v_add_f32_e32 v14, 0x4b400000, v15
	v_add_f32_e32 v15, 0x4b400000, v18
	v_add_f32_e32 v18, 0x4b400000, v19
	v_pk_mul_f32 v[12:13], v[12:13], v[162:163] op_sel_hi:[1,0]
	v_perm_b32 v15, v18, v15, s70
	v_perm_b32 v0, v14, v0, s70
	v_perm_b32 v14, v15, v0, s71
	v_add_f32_e32 v0, 0x4b400000, v12
	v_add_f32_e32 v12, 0x4b400000, v13
	v_add_f32_e32 v13, 0x4b400000, v16
	v_add_f32_e32 v15, 0x4b400000, v17
	v_perm_b32 v13, v15, v13, s70
	v_perm_b32 v0, v12, v0, s70
	v_pk_mul_f32 v[10:11], v[10:11], v[162:163] op_sel_hi:[1,0]
	v_pk_mul_f32 v[6:7], v[6:7], v[162:163] op_sel_hi:[1,0]
	global_store_dwordx2 v[2:3], v[26:27], off
	v_add_u32_e32 v2, s91, v176
	v_perm_b32 v15, v13, v0, s71
	v_add_f32_e32 v0, 0x4b400000, v6
	v_add_f32_e32 v6, 0x4b400000, v7
	v_add_f32_e32 v7, 0x4b400000, v10
	v_add_f32_e32 v10, 0x4b400000, v11
	v_ashrrev_i32_e32 v3, 31, v2
	v_lshlrev_b64 v[2:3], 10, v[2:3]
	v_pk_mul_f32 v[8:9], v[8:9], v[162:163] op_sel_hi:[1,0]
	v_pk_mul_f32 v[4:5], v[4:5], v[162:163] op_sel_hi:[1,0]
	v_perm_b32 v7, v10, v7, s70
	v_perm_b32 v0, v6, v0, s70
	v_lshl_add_u64 v[2:3], s[30:31], 0, v[2:3]
	v_perm_b32 v6, v7, v0, s71
	v_add_f32_e32 v0, 0x4b400000, v4
	v_add_f32_e32 v4, 0x4b400000, v5
	v_add_f32_e32 v5, 0x4b400000, v8
	v_add_f32_e32 v7, 0x4b400000, v9
	v_lshl_add_u64 v[2:3], v[2:3], 0, s[56:57]
	v_lshl_add_u64 v[2:3], v[2:3], 0, s[40:41]
	v_perm_b32 v5, v7, v5, s70
	v_perm_b32 v0, v4, v0, s70
	v_lshl_add_u64 v[2:3], v[2:3], 0, v[142:143]
	v_perm_b32 v7, v5, v0, s71
	global_store_dwordx2 v[2:3], v[14:15], off
	global_store_dwordx2 v[2:3], v[6:7], off offset:128

.LBB0_3273:
	s_or_b64 exec, exec, s[56:57]
	s_waitcnt lgkmcnt(0)
	s_barrier
	s_waitcnt lgkmcnt(1)
	v_lshlrev_b64 v[2:3], 10, v[148:149]
	ds_read_b32 v0, v180 offset:8192
	ds_read_b32 v148, v181 offset:8192
	s_waitcnt lgkmcnt(2)
	ds_read_b32 v152, v182 offset:8192
	ds_read_b32 v154, v183 offset:8192
	ds_read_b32 v156, v184 offset:8192
	ds_read_b32 v158, v185 offset:8192
	ds_read_b32 v160, v186 offset:8192
	ds_read_b32 v162, v187 offset:8192
	s_waitcnt lgkmcnt(7)
	v_pk_mul_f32 v[118:119], v[118:119], v[0:1] op_sel_hi:[1,0]
	v_pk_mul_f32 v[114:115], v[114:115], v[0:1] op_sel_hi:[1,0]
	v_pk_mul_f32 v[126:127], v[126:127], v[0:1] op_sel_hi:[1,0]
	v_pk_mul_f32 v[122:123], v[122:123], v[0:1] op_sel_hi:[1,0]
	v_pk_mul_f32 v[128:129], v[128:129], v[0:1] op_sel_hi:[1,0]
	v_pk_mul_f32 v[124:125], v[124:125], v[0:1] op_sel_hi:[1,0]
	v_pk_mul_f32 v[120:121], v[120:121], v[0:1] op_sel_hi:[1,0]
	v_pk_mul_f32 v[116:117], v[116:117], v[0:1] op_sel_hi:[1,0]
	v_add_f32_e32 v0, 0x4b400000, v114
	v_add_f32_e32 v114, 0x4b400000, v115
	v_add_f32_e32 v115, 0x4b400000, v118
	v_add_f32_e32 v118, 0x4b400000, v119
	v_perm_b32 v115, v118, v115, s71
	v_perm_b32 v0, v114, v0, s71
	v_perm_b32 v114, v115, v0, s72
	v_add_f32_e32 v0, 0x4b400000, v116
	v_add_f32_e32 v115, 0x4b400000, v117
	v_add_f32_e32 v116, 0x4b400000, v120
	v_add_f32_e32 v117, 0x4b400000, v121
	v_perm_b32 v116, v117, v116, s71
	v_perm_b32 v0, v115, v0, s71
	s_waitcnt lgkmcnt(6)
	v_pk_mul_f32 v[110:111], v[110:111], v[148:149] op_sel_hi:[1,0]
	v_pk_mul_f32 v[106:107], v[106:107], v[148:149] op_sel_hi:[1,0]
	v_perm_b32 v115, v116, v0, s72
	v_add_f32_e32 v0, 0x4b400000, v106
	v_add_f32_e32 v106, 0x4b400000, v107
	v_add_f32_e32 v107, 0x4b400000, v110
	v_add_f32_e32 v110, 0x4b400000, v111
	v_pk_mul_f32 v[112:113], v[112:113], v[148:149] op_sel_hi:[1,0]
	v_pk_mul_f32 v[108:109], v[108:109], v[148:149] op_sel_hi:[1,0]
	v_perm_b32 v107, v110, v107, s71
	v_perm_b32 v0, v106, v0, s71
	v_perm_b32 v106, v107, v0, s72
	v_add_f32_e32 v0, 0x4b400000, v108
	v_add_f32_e32 v107, 0x4b400000, v109
	v_add_f32_e32 v108, 0x4b400000, v112
	v_add_f32_e32 v109, 0x4b400000, v113
	v_perm_b32 v108, v109, v108, s71
	v_perm_b32 v0, v107, v0, s71
	v_pk_mul_f32 v[102:103], v[102:103], v[148:149] op_sel_hi:[1,0]
	v_pk_mul_f32 v[98:99], v[98:99], v[148:149] op_sel_hi:[1,0]
	v_perm_b32 v107, v108, v0, s72
	v_add_f32_e32 v0, 0x4b400000, v98
	v_add_f32_e32 v98, 0x4b400000, v99
	v_add_f32_e32 v99, 0x4b400000, v102
	v_add_f32_e32 v102, 0x4b400000, v103
	v_pk_mul_f32 v[104:105], v[104:105], v[148:149] op_sel_hi:[1,0]
	v_pk_mul_f32 v[100:101], v[100:101], v[148:149] op_sel_hi:[1,0]
	v_perm_b32 v99, v102, v99, s71
	v_perm_b32 v0, v98, v0, s71
	v_perm_b32 v98, v99, v0, s72
	v_add_f32_e32 v0, 0x4b400000, v100
	v_add_f32_e32 v99, 0x4b400000, v101
	v_add_f32_e32 v100, 0x4b400000, v104
	v_add_f32_e32 v101, 0x4b400000, v105
	v_perm_b32 v100, v101, v100, s71
	v_perm_b32 v0, v99, v0, s71
	s_waitcnt lgkmcnt(5)
	v_pk_mul_f32 v[94:95], v[94:95], v[152:153] op_sel_hi:[1,0]
	v_pk_mul_f32 v[90:91], v[90:91], v[152:153] op_sel_hi:[1,0]
	v_perm_b32 v99, v100, v0, s72
	v_add_f32_e32 v0, 0x4b400000, v90
	v_add_f32_e32 v90, 0x4b400000, v91
	v_add_f32_e32 v91, 0x4b400000, v94
	v_add_f32_e32 v94, 0x4b400000, v95
	v_pk_mul_f32 v[96:97], v[96:97], v[152:153] op_sel_hi:[1,0]
	v_pk_mul_f32 v[92:93], v[92:93], v[152:153] op_sel_hi:[1,0]
	v_perm_b32 v91, v94, v91, s71
	v_perm_b32 v0, v90, v0, s71
	v_perm_b32 v90, v91, v0, s72
	v_add_f32_e32 v0, 0x4b400000, v92
	v_add_f32_e32 v91, 0x4b400000, v93
	v_add_f32_e32 v92, 0x4b400000, v96
	v_add_f32_e32 v93, 0x4b400000, v97
	v_perm_b32 v92, v93, v92, s71
	v_perm_b32 v0, v91, v0, s71
	v_pk_mul_f32 v[86:87], v[86:87], v[152:153] op_sel_hi:[1,0]
	v_pk_mul_f32 v[82:83], v[82:83], v[152:153] op_sel_hi:[1,0]
	v_perm_b32 v91, v92, v0, s72
	v_add_f32_e32 v0, 0x4b400000, v82
	v_add_f32_e32 v82, 0x4b400000, v83
	v_add_f32_e32 v83, 0x4b400000, v86
	v_add_f32_e32 v86, 0x4b400000, v87
	v_pk_mul_f32 v[88:89], v[88:89], v[152:153] op_sel_hi:[1,0]
	v_pk_mul_f32 v[84:85], v[84:85], v[152:153] op_sel_hi:[1,0]
	v_perm_b32 v83, v86, v83, s71
	v_perm_b32 v0, v82, v0, s71
	v_perm_b32 v82, v83, v0, s72
	v_add_f32_e32 v0, 0x4b400000, v84
	v_add_f32_e32 v83, 0x4b400000, v85
	v_add_f32_e32 v84, 0x4b400000, v88
	v_add_f32_e32 v85, 0x4b400000, v89
	v_perm_b32 v84, v85, v84, s71
	v_perm_b32 v0, v83, v0, s71
	s_waitcnt lgkmcnt(4)
	v_pk_mul_f32 v[78:79], v[78:79], v[154:155] op_sel_hi:[1,0]
	v_pk_mul_f32 v[74:75], v[74:75], v[154:155] op_sel_hi:[1,0]
	v_add_f32_e32 v122, 0x4b400000, v122
	v_add_f32_e32 v123, 0x4b400000, v123
	v_add_f32_e32 v126, 0x4b400000, v126
	v_add_f32_e32 v127, 0x4b400000, v127
	v_perm_b32 v83, v84, v0, s72
	v_add_f32_e32 v0, 0x4b400000, v74
	v_add_f32_e32 v74, 0x4b400000, v75
	v_add_f32_e32 v75, 0x4b400000, v78
	v_add_f32_e32 v78, 0x4b400000, v79
	v_perm_b32 v126, v127, v126, s71
	v_perm_b32 v122, v123, v122, s71
	v_pk_mul_f32 v[80:81], v[80:81], v[154:155] op_sel_hi:[1,0]
	v_pk_mul_f32 v[76:77], v[76:77], v[154:155] op_sel_hi:[1,0]
	v_perm_b32 v75, v78, v75, s71
	v_perm_b32 v0, v74, v0, s71
	v_perm_b32 v122, v126, v122, s72
	v_add_f32_e32 v123, 0x4b400000, v124
	v_add_f32_e32 v124, 0x4b400000, v125
	v_add_f32_e32 v125, 0x4b400000, v128
	v_add_f32_e32 v126, 0x4b400000, v129
	v_lshl_add_u64 v[2:3], s[26:27], 0, v[2:3]
	v_perm_b32 v74, v75, v0, s72
	v_add_f32_e32 v0, 0x4b400000, v76
	v_add_f32_e32 v75, 0x4b400000, v77
	v_add_f32_e32 v76, 0x4b400000, v80
	v_add_f32_e32 v77, 0x4b400000, v81
	v_lshl_add_u64 v[2:3], v[2:3], 0, s[58:59]
	v_perm_b32 v125, v126, v125, s71
	v_perm_b32 v123, v124, v123, s71
	v_lshl_add_u64 v[2:3], v[2:3], 0, s[34:35]
	v_perm_b32 v76, v77, v76, s71
	v_perm_b32 v0, v75, v0, s71
	v_pk_mul_f32 v[70:71], v[70:71], v[154:155] op_sel_hi:[1,0]
	v_pk_mul_f32 v[66:67], v[66:67], v[154:155] op_sel_hi:[1,0]
	v_perm_b32 v123, v125, v123, s72
	v_lshl_add_u64 v[2:3], v[2:3], 0, v[142:143]
	v_perm_b32 v75, v76, v0, s72
	v_add_f32_e32 v0, 0x4b400000, v66
	v_add_f32_e32 v66, 0x4b400000, v67
	v_add_f32_e32 v67, 0x4b400000, v70
	v_add_f32_e32 v70, 0x4b400000, v71
	global_store_dwordx2 v[2:3], v[122:123], off
	global_store_dwordx2 v[2:3], v[114:115], off offset:128
	v_add_u32_e32 v2, s43, v171
	v_ashrrev_i32_e32 v3, 31, v2
	v_pk_mul_f32 v[72:73], v[72:73], v[154:155] op_sel_hi:[1,0]
	v_pk_mul_f32 v[68:69], v[68:69], v[154:155] op_sel_hi:[1,0]
	v_perm_b32 v67, v70, v67, s71
	v_perm_b32 v0, v66, v0, s71
	v_lshlrev_b64 v[2:3], 10, v[2:3]
	v_perm_b32 v66, v67, v0, s72
	v_add_f32_e32 v0, 0x4b400000, v68
	v_add_f32_e32 v67, 0x4b400000, v69
	v_add_f32_e32 v68, 0x4b400000, v72
	v_add_f32_e32 v69, 0x4b400000, v73
	v_lshl_add_u64 v[2:3], s[26:27], 0, v[2:3]
	v_lshl_add_u64 v[2:3], v[2:3], 0, s[58:59]
	v_perm_b32 v68, v69, v68, s71
	v_perm_b32 v0, v67, v0, s71
	s_waitcnt lgkmcnt(3)
	v_pk_mul_f32 v[62:63], v[62:63], v[156:157] op_sel_hi:[1,0]
	v_pk_mul_f32 v[58:59], v[58:59], v[156:157] op_sel_hi:[1,0]
	v_lshl_add_u64 v[2:3], v[2:3], 0, s[34:35]
	v_perm_b32 v67, v68, v0, s72
	v_add_f32_e32 v0, 0x4b400000, v58
	v_add_f32_e32 v58, 0x4b400000, v59
	v_add_f32_e32 v59, 0x4b400000, v62
	v_add_f32_e32 v62, 0x4b400000, v63
	v_lshl_add_u64 v[2:3], v[2:3], 0, v[142:143]
	global_store_dwordx2 v[2:3], v[106:107], off
	global_store_dwordx2 v[2:3], v[98:99], off offset:128
	v_add_u32_e32 v2, s43, v172
	v_pk_mul_f32 v[64:65], v[64:65], v[156:157] op_sel_hi:[1,0]
	v_pk_mul_f32 v[60:61], v[60:61], v[156:157] op_sel_hi:[1,0]
	v_perm_b32 v59, v62, v59, s71
	v_perm_b32 v0, v58, v0, s71
	v_ashrrev_i32_e32 v3, 31, v2
	v_perm_b32 v58, v59, v0, s72
	v_add_f32_e32 v0, 0x4b400000, v60
	v_add_f32_e32 v59, 0x4b400000, v61
	v_add_f32_e32 v60, 0x4b400000, v64
	v_add_f32_e32 v61, 0x4b400000, v65
	v_lshlrev_b64 v[2:3], 10, v[2:3]
	v_lshl_add_u64 v[2:3], s[26:27], 0, v[2:3]
	v_perm_b32 v60, v61, v60, s71
	v_perm_b32 v0, v59, v0, s71
	v_pk_mul_f32 v[54:55], v[54:55], v[156:157] op_sel_hi:[1,0]
	v_pk_mul_f32 v[50:51], v[50:51], v[156:157] op_sel_hi:[1,0]
	v_lshl_add_u64 v[2:3], v[2:3], 0, s[58:59]
	v_perm_b32 v59, v60, v0, s72
	v_add_f32_e32 v0, 0x4b400000, v50
	v_add_f32_e32 v50, 0x4b400000, v51
	v_add_f32_e32 v51, 0x4b400000, v54
	v_add_f32_e32 v54, 0x4b400000, v55
	v_lshl_add_u64 v[2:3], v[2:3], 0, s[34:35]
	v_lshl_add_u64 v[2:3], v[2:3], 0, v[142:143]
	v_pk_mul_f32 v[56:57], v[56:57], v[156:157] op_sel_hi:[1,0]
	v_pk_mul_f32 v[52:53], v[52:53], v[156:157] op_sel_hi:[1,0]
	v_perm_b32 v51, v54, v51, s71
	v_perm_b32 v0, v50, v0, s71
	global_store_dwordx2 v[2:3], v[90:91], off
	global_store_dwordx2 v[2:3], v[82:83], off offset:128
	v_add_u32_e32 v2, s43, v173
	v_perm_b32 v50, v51, v0, s72
	v_add_f32_e32 v0, 0x4b400000, v52
	v_add_f32_e32 v51, 0x4b400000, v53
	v_add_f32_e32 v52, 0x4b400000, v56
	v_add_f32_e32 v53, 0x4b400000, v57
	v_ashrrev_i32_e32 v3, 31, v2
	v_lshlrev_b64 v[2:3], 10, v[2:3]
	v_perm_b32 v52, v53, v52, s71
	v_perm_b32 v0, v51, v0, s71
	s_waitcnt lgkmcnt(2)
	v_pk_mul_f32 v[46:47], v[46:47], v[158:159] op_sel_hi:[1,0]
	v_pk_mul_f32 v[42:43], v[42:43], v[158:159] op_sel_hi:[1,0]
	v_lshl_add_u64 v[2:3], s[26:27], 0, v[2:3]
	v_perm_b32 v51, v52, v0, s72
	v_add_f32_e32 v0, 0x4b400000, v42
	v_add_f32_e32 v42, 0x4b400000, v43
	v_add_f32_e32 v43, 0x4b400000, v46
	v_add_f32_e32 v46, 0x4b400000, v47
	v_lshl_add_u64 v[2:3], v[2:3], 0, s[58:59]
	v_lshl_add_u64 v[2:3], v[2:3], 0, s[34:35]
	v_pk_mul_f32 v[48:49], v[48:49], v[158:159] op_sel_hi:[1,0]
	v_pk_mul_f32 v[44:45], v[44:45], v[158:159] op_sel_hi:[1,0]
	v_perm_b32 v43, v46, v43, s71
	v_perm_b32 v0, v42, v0, s71
	v_lshl_add_u64 v[2:3], v[2:3], 0, v[142:143]
	v_perm_b32 v42, v43, v0, s72
	v_add_f32_e32 v0, 0x4b400000, v44
	v_add_f32_e32 v43, 0x4b400000, v45
	v_add_f32_e32 v44, 0x4b400000, v48
	v_add_f32_e32 v45, 0x4b400000, v49
	global_store_dwordx2 v[2:3], v[74:75], off
	global_store_dwordx2 v[2:3], v[66:67], off offset:128
	v_add_u32_e32 v2, s43, v170
	v_ashrrev_i32_e32 v3, 31, v2
	v_perm_b32 v44, v45, v44, s71
	v_perm_b32 v0, v43, v0, s71
	v_pk_mul_f32 v[38:39], v[38:39], v[158:159] op_sel_hi:[1,0]
	v_pk_mul_f32 v[34:35], v[34:35], v[158:159] op_sel_hi:[1,0]
	v_lshlrev_b64 v[2:3], 10, v[2:3]
	v_perm_b32 v43, v44, v0, s72
	v_add_f32_e32 v0, 0x4b400000, v34
	v_add_f32_e32 v34, 0x4b400000, v35
	v_add_f32_e32 v35, 0x4b400000, v38
	v_add_f32_e32 v38, 0x4b400000, v39
	v_lshl_add_u64 v[2:3], s[26:27], 0, v[2:3]
	v_lshl_add_u64 v[2:3], v[2:3], 0, s[58:59]
	v_pk_mul_f32 v[40:41], v[40:41], v[158:159] op_sel_hi:[1,0]
	v_pk_mul_f32 v[36:37], v[36:37], v[158:159] op_sel_hi:[1,0]
	v_perm_b32 v35, v38, v35, s71
	v_perm_b32 v0, v34, v0, s71
	v_lshl_add_u64 v[2:3], v[2:3], 0, s[34:35]
	v_perm_b32 v34, v35, v0, s72
	v_add_f32_e32 v0, 0x4b400000, v36
	v_add_f32_e32 v35, 0x4b400000, v37
	v_add_f32_e32 v36, 0x4b400000, v40
	v_add_f32_e32 v37, 0x4b400000, v41
	v_lshl_add_u64 v[2:3], v[2:3], 0, v[142:143]
	global_store_dwordx2 v[2:3], v[58:59], off
	global_store_dwordx2 v[2:3], v[50:51], off offset:128
	v_add_u32_e32 v2, s43, v174
	v_perm_b32 v36, v37, v36, s71
	v_perm_b32 v0, v35, v0, s71
	s_waitcnt lgkmcnt(1)
	v_pk_mul_f32 v[30:31], v[30:31], v[160:161] op_sel_hi:[1,0]
	v_pk_mul_f32 v[26:27], v[26:27], v[160:161] op_sel_hi:[1,0]
	v_ashrrev_i32_e32 v3, 31, v2
	v_perm_b32 v35, v36, v0, s72
	v_add_f32_e32 v0, 0x4b400000, v26
	v_add_f32_e32 v26, 0x4b400000, v27
	v_add_f32_e32 v27, 0x4b400000, v30
	v_add_f32_e32 v30, 0x4b400000, v31
	v_lshlrev_b64 v[2:3], 10, v[2:3]
	v_lshl_add_u64 v[2:3], s[26:27], 0, v[2:3]
	v_pk_mul_f32 v[32:33], v[32:33], v[160:161] op_sel_hi:[1,0]
	v_pk_mul_f32 v[28:29], v[28:29], v[160:161] op_sel_hi:[1,0]
	v_perm_b32 v27, v30, v27, s71
	v_perm_b32 v0, v26, v0, s71
	v_lshl_add_u64 v[2:3], v[2:3], 0, s[58:59]
	v_perm_b32 v26, v27, v0, s72
	v_add_f32_e32 v0, 0x4b400000, v28
	v_add_f32_e32 v27, 0x4b400000, v29
	v_add_f32_e32 v28, 0x4b400000, v32
	v_add_f32_e32 v29, 0x4b400000, v33
	v_lshl_add_u64 v[2:3], v[2:3], 0, s[34:35]
	v_lshl_add_u64 v[2:3], v[2:3], 0, v[142:143]
	v_perm_b32 v28, v29, v28, s71
	v_perm_b32 v0, v27, v0, s71
	v_pk_mul_f32 v[22:23], v[22:23], v[160:161] op_sel_hi:[1,0]
	v_pk_mul_f32 v[18:19], v[18:19], v[160:161] op_sel_hi:[1,0]
	global_store_dwordx2 v[2:3], v[42:43], off
	global_store_dwordx2 v[2:3], v[34:35], off offset:128
	v_add_u32_e32 v2, s43, v175
	v_perm_b32 v27, v28, v0, s72
	v_add_f32_e32 v0, 0x4b400000, v18
	v_add_f32_e32 v18, 0x4b400000, v19
	v_add_f32_e32 v19, 0x4b400000, v22
	v_add_f32_e32 v22, 0x4b400000, v23
	v_ashrrev_i32_e32 v3, 31, v2
	v_lshlrev_b64 v[2:3], 10, v[2:3]
	v_pk_mul_f32 v[24:25], v[24:25], v[160:161] op_sel_hi:[1,0]
	v_pk_mul_f32 v[20:21], v[20:21], v[160:161] op_sel_hi:[1,0]
	v_perm_b32 v19, v22, v19, s71
	v_perm_b32 v0, v18, v0, s71
	v_lshl_add_u64 v[2:3], s[26:27], 0, v[2:3]
	v_perm_b32 v18, v19, v0, s72
	v_add_f32_e32 v0, 0x4b400000, v20
	v_add_f32_e32 v19, 0x4b400000, v21
	v_add_f32_e32 v20, 0x4b400000, v24
	v_add_f32_e32 v21, 0x4b400000, v25
	v_lshl_add_u64 v[2:3], v[2:3], 0, s[58:59]
	v_lshl_add_u64 v[2:3], v[2:3], 0, s[34:35]
	v_perm_b32 v20, v21, v20, s71
	v_perm_b32 v0, v19, v0, s71
	v_lshl_add_u64 v[2:3], v[2:3], 0, v[142:143]
	v_perm_b32 v19, v20, v0, s72
	global_store_dwordx2 v[2:3], v[18:19], off offset:128
	s_waitcnt lgkmcnt(0)
	v_pk_mul_f32 v[18:19], v[150:151], v[162:163] op_sel_hi:[1,0]
	v_pk_mul_f32 v[14:15], v[14:15], v[162:163] op_sel_hi:[1,0]
	v_pk_mul_f32 v[16:17], v[16:17], v[162:163] op_sel_hi:[1,0]
	v_add_f32_e32 v0, 0x4b400000, v14
	v_add_f32_e32 v14, 0x4b400000, v15
	v_add_f32_e32 v15, 0x4b400000, v18
	v_add_f32_e32 v18, 0x4b400000, v19
	v_pk_mul_f32 v[12:13], v[12:13], v[162:163] op_sel_hi:[1,0]
	v_perm_b32 v15, v18, v15, s71
	v_perm_b32 v0, v14, v0, s71
	v_perm_b32 v14, v15, v0, s72
	v_add_f32_e32 v0, 0x4b400000, v12
	v_add_f32_e32 v12, 0x4b400000, v13
	v_add_f32_e32 v13, 0x4b400000, v16
	v_add_f32_e32 v15, 0x4b400000, v17
	v_perm_b32 v13, v15, v13, s71
	v_perm_b32 v0, v12, v0, s71
	v_pk_mul_f32 v[10:11], v[10:11], v[162:163] op_sel_hi:[1,0]
	v_pk_mul_f32 v[6:7], v[6:7], v[162:163] op_sel_hi:[1,0]
	global_store_dwordx2 v[2:3], v[26:27], off
	v_add_u32_e32 v2, s43, v176
	v_perm_b32 v15, v13, v0, s72
	v_add_f32_e32 v0, 0x4b400000, v6
	v_add_f32_e32 v6, 0x4b400000, v7
	v_add_f32_e32 v7, 0x4b400000, v10
	v_add_f32_e32 v10, 0x4b400000, v11
	v_ashrrev_i32_e32 v3, 31, v2
	v_lshlrev_b64 v[2:3], 10, v[2:3]
	v_pk_mul_f32 v[8:9], v[8:9], v[162:163] op_sel_hi:[1,0]
	v_pk_mul_f32 v[4:5], v[4:5], v[162:163] op_sel_hi:[1,0]
	v_perm_b32 v7, v10, v7, s71
	v_perm_b32 v0, v6, v0, s71
	v_lshl_add_u64 v[2:3], s[26:27], 0, v[2:3]
	v_perm_b32 v6, v7, v0, s72
	v_add_f32_e32 v0, 0x4b400000, v4
	v_add_f32_e32 v4, 0x4b400000, v5
	v_add_f32_e32 v5, 0x4b400000, v8
	v_add_f32_e32 v7, 0x4b400000, v9
	v_lshl_add_u64 v[2:3], v[2:3], 0, s[58:59]
	v_lshl_add_u64 v[2:3], v[2:3], 0, s[34:35]
	v_perm_b32 v5, v7, v5, s71
	v_perm_b32 v0, v4, v0, s71
	v_lshl_add_u64 v[2:3], v[2:3], 0, v[142:143]
	v_perm_b32 v7, v5, v0, s72
	global_store_dwordx2 v[2:3], v[14:15], off
	global_store_dwordx2 v[2:3], v[6:7], off offset:128
